# EpiUp: adjacent scalar silu muls/adds packed into v_pk_mul/v_pk_add (26+25 pairs), on top of dpp fusion
# baseline (speedup 1.0000x reference)
.LBB0_400:
	s_mov_b32 s100, 0xbfb8aa3b
	s_or_b64 exec, exec, s[38:39]
	s_ashr_i32 s27, s26, 31
	s_lshl_b64 s[4:5], s[26:27], 7
	v_lshl_add_u64 v[234:235], s[4:5], 0, v[138:139]
	v_lshl_add_u64 v[86:87], v[234:235], 2, s[48:49]
	v_add_co_u32_e32 v78, vcc, 0x5000, v86
	s_waitcnt lgkmcnt(0)
	s_barrier
	s_nop 0
	v_addc_co_u32_e32 v79, vcc, 0, v87, vcc
	global_load_dwordx4 v[158:161], v[86:87], off
	global_load_dwordx4 v[162:165], v[78:79], off offset:2048
	v_add_co_u32_e32 v78, vcc, 0xb000, v86
	v_mov_b32_dpp v90, v135 row_shr:1 row_mask:0xf bank_mask:0xf bound_ctrl:1
	s_nop 0
	v_addc_co_u32_e32 v79, vcc, 0, v87, vcc
	v_add_co_u32_e32 v80, vcc, s80, v86
	v_mov_b32_dpp v91, v144 row_shr:1 row_mask:0xf bank_mask:0xf bound_ctrl:1
	s_nop 0
	v_addc_co_u32_e32 v81, vcc, 0, v87, vcc
	v_add_co_u32_e32 v88, vcc, s64, v86
	global_load_dwordx4 v[174:177], v[78:79], off
	global_load_dwordx4 v[138:141], v[80:81], off offset:3072
	v_addc_co_u32_e32 v89, vcc, 0, v87, vcc
	v_add_co_u32_e32 v78, vcc, 0xd000, v86
	v_mov_b32_dpp v80, v134 row_shr:1 row_mask:0xf bank_mask:0xf bound_ctrl:1
	s_nop 0
	v_addc_co_u32_e32 v79, vcc, 0, v87, vcc
	global_load_dwordx4 v[146:149], v[88:89], off offset:1024
	global_load_dwordx4 v[150:153], v[78:79], off offset:3072
	v_lshlrev_b32_e32 v78, 7, v167
	v_mov_b32_dpp v79, v142 row_shr:1 row_mask:0xf bank_mask:0xf bound_ctrl:1
	v_mov_b32_dpp v81, v143 row_shr:1 row_mask:0xf bank_mask:0xf bound_ctrl:1
	v_mov_b32_dpp v92, v136 row_shr:1 row_mask:0xf bank_mask:0xf bound_ctrl:1
	v_mov_b32_dpp v93, v145 row_shr:1 row_mask:0xf bank_mask:0xf bound_ctrl:1
	v_mov_b32_dpp v94, v137 row_shr:1 row_mask:0xf bank_mask:0xf bound_ctrl:1
	v_cmp_ne_u32_e64 s[42:43], 0, v166
	s_nor_b64 s[26:27], s[52:53], s[42:43]
	v_add_u32_e32 v233, s97, v78
	v_cndmask_b32_e64 v185, 0, v93, s[42:43]
	v_cndmask_b32_e64 v184, 0, v91, s[42:43]
	v_cndmask_b32_e64 v183, 0, v81, s[42:43]
	v_cndmask_b32_e64 v182, 0, v79, s[42:43]
	v_cndmask_b32_e64 v189, 0, v94, s[42:43]
	v_cndmask_b32_e64 v188, 0, v92, s[42:43]
	v_cndmask_b32_e64 v187, 0, v90, s[42:43]
	v_cndmask_b32_e64 v186, 0, v80, s[42:43]
	s_and_saveexec_b64 s[38:39], s[26:27]
	s_cbranch_execz .LBB0_402
	ds_read_b128 v[186:189], v233
	ds_read_b128 v[182:185], v233 offset:64

.LBB0_408:
	s_or_b64 exec, exec, s[38:39]
	s_mov_b32 s4, 0x358637bd
	v_pk_add_f32 v[240:241], v[240:241], v[242:243]
	v_mov_b64_e32 v[214:215], s[4:5]
	v_pk_fma_f32 v[240:241], v[240:241], s[90:91], v[214:215] op_sel_hi:[1,0,0]
	v_pk_add_f32 v[236:237], v[236:237], v[238:239]
	v_mul_f32_e32 v216, 0x4b800000, v240
	v_cmp_gt_f32_e64 s[42:43], s10, v240
	v_cmp_gt_f32_e32 vcc, s10, v241
	v_pk_fma_f32 v[214:215], v[236:237], s[90:91], v[214:215] op_sel_hi:[1,0,0]
	v_cndmask_b32_e64 v216, v240, v216, s[42:43]
	v_rsq_f32_e32 v216, v216
	s_mov_b64 s[26:27], -1
	v_mul_f32_e32 v217, 0x45800000, v216
	v_cndmask_b32_e64 v240, v216, v217, s[42:43]
	v_mul_f32_e32 v216, 0x4b800000, v241
	v_cndmask_b32_e32 v216, v241, v216, vcc
	v_rsq_f32_e32 v216, v216
	v_cmp_gt_f32_e64 s[42:43], s10, v214
	v_pk_mul_f32 v[16:17], v[16:17], v[240:241] op_sel_hi:[1,0]
	v_mul_f32_e32 v217, 0x45800000, v216
	v_cndmask_b32_e32 v242, v216, v217, vcc
	v_mul_f32_e32 v216, 0x4b800000, v214
	v_cndmask_b32_e64 v214, v214, v216, s[42:43]
	v_rsq_f32_e32 v214, v214
	v_cmp_gt_f32_e32 vcc, s10, v215
	v_pk_mul_f32 v[220:221], v[68:69], v[242:243] op_sel_hi:[1,0]
	v_pk_mul_f32 v[218:219], v[66:67], v[242:243] op_sel_hi:[1,0]
	v_mul_f32_e32 v216, 0x45800000, v214
	v_cndmask_b32_e64 v236, v214, v216, s[42:43]
	v_mul_f32_e32 v214, 0x4b800000, v215
	v_cndmask_b32_e32 v214, v215, v214, vcc
	v_rsq_f32_e32 v214, v214
	v_pk_mul_f32 v[216:217], v[72:73], v[240:241] op_sel_hi:[1,0]
	v_pk_mul_f32 v[72:73], v[64:65], v[236:237] op_sel_hi:[1,0]
	s_waitcnt vmcnt(3)
	v_pk_mul_f32 v[64:65], v[154:155], v[198:199]
	v_mul_f32_e32 v215, 0x45800000, v214
	v_cndmask_b32_e32 v238, v214, v215, vcc
	v_pk_mul_f32 v[68:69], v[60:61], v[238:239] op_sel_hi:[1,0]
	v_pk_mul_f32 v[60:61], v[178:179], v[198:199]
	v_pk_mul_f32 v[66:67], v[58:59], v[238:239] op_sel_hi:[1,0]
	v_pk_mul_f32 v[58:59], v[180:181], v[200:201]
	v_pk_fma_f32 v[60:61], v[154:155], v[194:195], v[60:61]
	v_pk_mul_f32 v[214:215], v[70:71], v[240:241] op_sel_hi:[1,0]
	v_pk_mul_f32 v[70:71], v[62:63], v[236:237] op_sel_hi:[1,0]
	v_pk_fma_f32 v[58:59], v[156:157], v[196:197], v[58:59]
	v_pk_fma_f32 v[60:61], v[66:67], v[190:191], v[60:61]
	v_pk_mul_f32 v[62:63], v[156:157], v[200:201]
	v_pk_fma_f32 v[64:65], v[66:67], v[194:195], v[64:65]
	v_pk_mul_f32 v[66:67], v[66:67], v[198:199]
	v_pk_fma_f32 v[58:59], v[68:69], v[192:193], v[58:59]
	v_pk_fma_f32 v[62:63], v[68:69], v[196:197], v[62:63]
	v_pk_fma_f32 v[64:65], v[70:71], v[190:191], v[64:65]
	v_pk_mul_f32 v[68:69], v[68:69], v[200:201]
	v_pk_fma_f32 v[154:155], v[70:71], v[194:195], v[66:67]
	v_pk_mul_f32 v[70:71], v[70:71], v[198:199]
	v_pk_fma_f32 v[62:63], v[72:73], v[192:193], v[62:63]
	v_pk_fma_f32 v[66:67], v[72:73], v[196:197], v[68:69]
	v_pk_fma_f32 v[68:69], v[218:219], v[190:191], v[154:155]
	v_pk_mul_f32 v[72:73], v[72:73], v[200:201]
	v_pk_fma_f32 v[154:155], v[218:219], v[194:195], v[70:71]
	v_pk_fma_f32 v[70:71], v[220:221], v[196:197], v[72:73]
	v_pk_fma_f32 v[72:73], v[214:215], v[190:191], v[154:155]
	v_pk_mul_f32 v[154:155], v[220:221], v[200:201]
	v_pk_mul_f32 v[156:157], v[218:219], v[198:199]
	v_pk_fma_f32 v[154:155], v[216:217], v[196:197], v[154:155]
	v_pk_fma_f32 v[156:157], v[214:215], v[194:195], v[156:157]
	v_pk_mul_f32 v[178:179], v[216:217], v[200:201]
	v_pk_mul_f32 v[180:181], v[214:215], v[198:199]
	v_pk_fma_f32 v[154:155], v[128:129], v[192:193], v[154:155]
	v_pk_fma_f32 v[156:157], v[126:127], v[190:191], v[156:157]
	v_pk_fma_f32 v[180:181], v[126:127], v[194:195], v[180:181]
	v_pk_fma_f32 v[178:179], v[128:129], v[196:197], v[178:179]
	v_pk_mul_f32 v[128:129], v[128:129], v[200:201]
	v_pk_mul_f32 v[126:127], v[126:127], v[198:199]
	v_pk_fma_f32 v[128:129], v[124:125], v[196:197], v[128:129]
	v_pk_fma_f32 v[214:215], v[122:123], v[194:195], v[126:127]
	s_waitcnt lgkmcnt(0)
	v_pk_mul_f32 v[196:197], v[196:197], v[204:205]
	v_pk_mul_f32 v[194:195], v[194:195], v[202:203]
	v_pk_fma_f32 v[178:179], v[124:125], v[192:193], v[178:179]
	v_pk_fma_f32 v[124:125], v[124:125], v[200:201], v[196:197]
	v_pk_fma_f32 v[194:195], v[122:123], v[198:199], v[194:195]
	v_pk_mul_f32 v[198:199], v[38:39], v[236:237] op_sel_hi:[1,0]
	v_pk_mul_f32 v[200:201], v[40:41], v[236:237] op_sel_hi:[1,0]
	v_pk_mul_f32 v[38:39], v[144:145], v[176:177]
	v_pk_mul_f32 v[40:41], v[142:143], v[174:175]
	v_pk_mul_f32 v[34:35], v[34:35], v[238:239] op_sel_hi:[1,0]
	v_pk_mul_f32 v[36:37], v[36:37], v[238:239] op_sel_hi:[1,0]
	v_pk_fma_f32 v[38:39], v[136:137], v[164:165], v[38:39]
	v_pk_fma_f32 v[40:41], v[134:135], v[162:163], v[40:41]
	v_pk_fma_f32 v[66:67], v[220:221], v[192:193], v[66:67]
	v_pk_fma_f32 v[70:71], v[216:217], v[192:193], v[70:71]
	v_pk_fma_f32 v[180:181], v[122:123], v[190:191], v[180:181]
	v_pk_fma_f32 v[126:127], v[192:193], v[204:205], v[128:129]
	v_pk_fma_f32 v[128:129], v[190:191], v[202:203], v[214:215]
	v_pk_fma_f32 v[122:123], v[192:193], v[208:209], v[124:125]
	v_pk_fma_f32 v[124:125], v[190:191], v[206:207], v[194:195]
	v_pk_mul_f32 v[190:191], v[54:55], v[240:241] op_sel_hi:[1,0]
	v_pk_mul_f32 v[192:193], v[56:57], v[240:241] op_sel_hi:[1,0]
	v_pk_fma_f32 v[56:57], v[36:37], v[160:161], v[38:39]
	v_pk_fma_f32 v[54:55], v[34:35], v[158:159], v[40:41]
	v_pk_mul_f32 v[38:39], v[136:137], v[176:177]
	v_pk_mul_f32 v[40:41], v[134:135], v[174:175]
	v_pk_fma_f32 v[38:39], v[36:37], v[164:165], v[38:39]
	v_pk_fma_f32 v[40:41], v[34:35], v[162:163], v[40:41]
	v_pk_mul_f32 v[36:37], v[36:37], v[176:177]
	v_pk_mul_f32 v[34:35], v[34:35], v[174:175]
	v_pk_mul_f32 v[194:195], v[50:51], v[242:243] op_sel_hi:[1,0]
	v_pk_mul_f32 v[196:197], v[52:53], v[242:243] op_sel_hi:[1,0]
	v_pk_fma_f32 v[34:35], v[198:199], v[162:163], v[34:35]
	v_pk_fma_f32 v[36:37], v[200:201], v[164:165], v[36:37]
	v_pk_fma_f32 v[52:53], v[200:201], v[160:161], v[38:39]
	v_pk_fma_f32 v[50:51], v[198:199], v[158:159], v[40:41]
	v_pk_fma_f32 v[40:41], v[196:197], v[160:161], v[36:37]
	v_pk_fma_f32 v[38:39], v[194:195], v[158:159], v[34:35]
	v_pk_mul_f32 v[34:35], v[200:201], v[176:177]
	v_pk_mul_f32 v[36:37], v[198:199], v[174:175]
	v_pk_fma_f32 v[34:35], v[196:197], v[164:165], v[34:35]
	v_pk_fma_f32 v[134:135], v[194:195], v[162:163], v[36:37]
	v_pk_mul_f32 v[136:137], v[194:195], v[174:175]
	v_pk_fma_f32 v[36:37], v[192:193], v[160:161], v[34:35]
	v_pk_fma_f32 v[34:35], v[190:191], v[158:159], v[134:135]
	v_pk_mul_f32 v[134:135], v[196:197], v[176:177]
	v_pk_fma_f32 v[136:137], v[190:191], v[162:163], v[136:137]
	v_pk_mul_f32 v[144:145], v[190:191], v[174:175]
	v_pk_fma_f32 v[134:135], v[192:193], v[164:165], v[134:135]
	v_pk_fma_f32 v[136:137], v[118:119], v[158:159], v[136:137]
	v_pk_mul_f32 v[142:143], v[192:193], v[176:177]
	v_pk_fma_f32 v[144:145], v[118:119], v[162:163], v[144:145]
	v_pk_mul_f32 v[118:119], v[118:119], v[174:175]
	v_pk_fma_f32 v[134:135], v[120:121], v[160:161], v[134:135]
	v_pk_fma_f32 v[142:143], v[120:121], v[164:165], v[142:143]
	v_pk_mul_f32 v[120:121], v[120:121], v[176:177]
	v_pk_fma_f32 v[118:119], v[114:115], v[162:163], v[118:119]
	v_pk_fma_f32 v[120:121], v[116:117], v[164:165], v[120:121]
	v_pk_fma_f32 v[192:193], v[158:159], v[182:183], v[118:119]
	v_pk_mul_f32 v[118:119], v[164:165], v[184:185]
	v_pk_mul_f32 v[164:165], v[30:31], v[240:241] op_sel_hi:[1,0]
	v_pk_mul_f32 v[30:31], v[132:133], v[152:153]
	v_pk_fma_f32 v[142:143], v[116:117], v[160:161], v[142:143]
	v_pk_fma_f32 v[116:117], v[116:117], v[176:177], v[118:119]
	v_pk_mul_f32 v[20:21], v[20:21], v[238:239] op_sel_hi:[1,0]
	v_pk_fma_f32 v[30:31], v[104:105], v[148:149], v[30:31]
	v_pk_fma_f32 v[190:191], v[160:161], v[184:185], v[120:121]
	v_pk_fma_f32 v[160:161], v[160:161], v[188:189], v[116:117]
	v_pk_fma_f32 v[116:117], v[20:21], v[140:141], v[30:31]
	v_pk_mul_f32 v[30:31], v[104:105], v[152:153]
	v_pk_mul_f32 v[120:121], v[162:163], v[182:183]
	v_pk_mul_f32 v[162:163], v[32:33], v[240:241] op_sel_hi:[1,0]
	v_pk_mul_f32 v[24:25], v[24:25], v[236:237] op_sel_hi:[1,0]
	v_pk_mul_f32 v[32:33], v[130:131], v[150:151]
	v_pk_fma_f32 v[30:31], v[20:21], v[148:149], v[30:31]
	v_pk_mul_f32 v[20:21], v[20:21], v[152:153]
	v_pk_fma_f32 v[144:145], v[114:115], v[158:159], v[144:145]
	v_pk_fma_f32 v[114:115], v[114:115], v[174:175], v[120:121]
	v_pk_mul_f32 v[28:29], v[28:29], v[242:243] op_sel_hi:[1,0]
	v_pk_mul_f32 v[18:19], v[18:19], v[238:239] op_sel_hi:[1,0]
	v_pk_fma_f32 v[32:33], v[102:103], v[146:147], v[32:33]
	v_pk_fma_f32 v[20:21], v[24:25], v[148:149], v[20:21]
	v_pk_fma_f32 v[158:159], v[158:159], v[186:187], v[114:115]
	v_pk_fma_f32 v[114:115], v[18:19], v[138:139], v[32:33]
	v_pk_mul_f32 v[32:33], v[102:103], v[150:151]
	v_pk_fma_f32 v[120:121], v[28:29], v[140:141], v[20:21]
	v_pk_mul_f32 v[20:21], v[24:25], v[152:153]
	v_pk_mul_f32 v[22:23], v[22:23], v[236:237] op_sel_hi:[1,0]
	v_pk_fma_f32 v[32:33], v[18:19], v[146:147], v[32:33]
	v_pk_mul_f32 v[18:19], v[18:19], v[150:151]
	v_pk_fma_f32 v[20:21], v[28:29], v[148:149], v[20:21]
	v_pk_mul_f32 v[26:27], v[26:27], v[242:243] op_sel_hi:[1,0]
	v_pk_fma_f32 v[18:19], v[22:23], v[146:147], v[18:19]
	v_pk_fma_f32 v[132:133], v[162:163], v[140:141], v[20:21]
	v_pk_mul_f32 v[20:21], v[28:29], v[152:153]
	v_pk_fma_f32 v[118:119], v[26:27], v[138:139], v[18:19]
	v_pk_mul_f32 v[18:19], v[22:23], v[150:151]
	v_pk_fma_f32 v[20:21], v[162:163], v[148:149], v[20:21]
	v_pk_fma_f32 v[102:103], v[22:23], v[138:139], v[32:33]
	v_pk_fma_f32 v[18:19], v[26:27], v[146:147], v[18:19]
	v_pk_fma_f32 v[32:33], v[112:113], v[140:141], v[20:21]
	v_pk_mul_f32 v[20:21], v[162:163], v[152:153]
	v_pk_fma_f32 v[130:131], v[164:165], v[138:139], v[18:19]
	v_pk_mul_f32 v[18:19], v[26:27], v[150:151]
	v_pk_fma_f32 v[20:21], v[112:113], v[148:149], v[20:21]
	v_pk_fma_f32 v[18:19], v[164:165], v[146:147], v[18:19]
	v_pk_fma_f32 v[28:29], v[108:109], v[140:141], v[20:21]
	v_pk_mul_f32 v[20:21], v[110:111], v[150:151]
	v_pk_fma_f32 v[104:105], v[24:25], v[140:141], v[30:31]
	v_pk_fma_f32 v[30:31], v[110:111], v[138:139], v[18:19]
	v_pk_mul_f32 v[18:19], v[164:165], v[150:151]
	v_pk_fma_f32 v[20:21], v[106:107], v[146:147], v[20:21]
	v_pk_fma_f32 v[18:19], v[110:111], v[146:147], v[18:19]
	v_pk_fma_f32 v[24:25], v[138:139], v[166:167], v[20:21]
	v_pk_mul_f32 v[20:21], v[146:147], v[166:167]
	v_pk_fma_f32 v[26:27], v[106:107], v[138:139], v[18:19]
	v_pk_fma_f32 v[20:21], v[106:107], v[150:151], v[20:21]
	v_pk_mul_f32 v[106:107], v[158:159], s[100:101] op_sel_hi:[1,0]
	v_exp_f32_e32 v106, v106
	v_exp_f32_e32 v107, v107
	v_pk_mul_f32 v[18:19], v[112:113], v[152:153]
	v_pk_fma_f32 v[20:21], v[138:139], v[170:171], v[20:21]
	v_pk_fma_f32 v[18:19], v[108:109], v[148:149], v[18:19]
	v_pk_add_f32 v[106:107], v[106:107], 1.0 op_sel_hi:[1,0]
	v_pk_fma_f32 v[22:23], v[140:141], v[168:169], v[18:19]
	v_pk_mul_f32 v[18:19], v[148:149], v[168:169]
	v_rcp_f32_e32 v106, v106
	v_rcp_f32_e32 v107, v107
	v_pk_fma_f32 v[18:19], v[108:109], v[152:153], v[18:19]
	v_pk_mul_f32 v[26:27], v[144:145], v[26:27]
	v_pk_fma_f32 v[18:19], v[140:141], v[172:173], v[18:19]
	v_pk_mul_f32 v[28:29], v[142:143], v[28:29]
	v_pk_mul_f32 v[108:109], v[160:161], v[18:19]
	v_pk_mul_f32 v[18:19], v[158:159], v[20:21]
	v_pk_mul_f32 v[20:21], v[160:161], s[100:101] op_sel_hi:[1,0]
	v_pk_mul_f32 v[18:19], v[106:107], v[18:19]
	v_exp_f32_e32 v20, v20
	v_exp_f32_e32 v21, v21
	v_pk_mul_f32 v[106:107], v[192:193], s[100:101] op_sel_hi:[1,0]
	v_exp_f32_e32 v106, v106
	v_exp_f32_e32 v107, v107
	v_pk_add_f32 v[20:21], v[20:21], 1.0 op_sel_hi:[1,0]
	v_rcp_f32_e32 v20, v20
	v_rcp_f32_e32 v21, v21
	v_pk_add_f32 v[106:107], v[106:107], 1.0 op_sel_hi:[1,0]
	v_rcp_f32_e32 v106, v106
	v_rcp_f32_e32 v107, v107
	v_pk_mul_f32 v[20:21], v[20:21], v[108:109]
	v_pk_mul_f32 v[108:109], v[190:191], v[22:23]
	v_pk_mul_f32 v[22:23], v[192:193], v[24:25]
	v_pk_mul_f32 v[30:31], v[136:137], v[30:31]
	v_pk_mul_f32 v[22:23], v[106:107], v[22:23]
	v_pk_mul_f32 v[106:107], v[144:145], s[100:101] op_sel_hi:[1,0]
	v_exp_f32_e32 v106, v106
	v_exp_f32_e32 v107, v107
	v_pk_mul_f32 v[24:25], v[190:191], s[100:101] op_sel_hi:[1,0]
	v_pk_add_f32 v[106:107], v[106:107], 1.0 op_sel_hi:[1,0]
	v_rcp_f32_e32 v106, v106
	v_rcp_f32_e32 v107, v107
	v_pk_mul_f32 v[32:33], v[134:135], v[32:33]
	v_exp_f32_e32 v24, v24
	v_exp_f32_e32 v25, v25
	v_pk_mul_f32 v[26:27], v[106:107], v[26:27]
	v_pk_mul_f32 v[106:107], v[142:143], s[100:101] op_sel_hi:[1,0]
	v_exp_f32_e32 v106, v106
	v_exp_f32_e32 v107, v107
	v_pk_add_f32 v[24:25], v[24:25], 1.0 op_sel_hi:[1,0]
	v_pk_add_f32 v[106:107], v[106:107], 1.0 op_sel_hi:[1,0]
	v_rcp_f32_e32 v106, v106
	v_rcp_f32_e32 v107, v107
	v_rcp_f32_e32 v24, v24
	v_rcp_f32_e32 v25, v25
	v_pk_mul_f32 v[104:105], v[52:53], v[104:105]
	v_pk_mul_f32 v[28:29], v[106:107], v[28:29]
	v_pk_mul_f32 v[106:107], v[136:137], s[100:101] op_sel_hi:[1,0]
	v_exp_f32_e32 v106, v106
	v_exp_f32_e32 v107, v107
	v_pk_mul_f32 v[24:25], v[24:25], v[108:109]
	v_pk_mul_f32 v[108:109], v[36:37], v[132:133]
	v_pk_add_f32 v[106:107], v[106:107], 1.0 op_sel_hi:[1,0]
	v_rcp_f32_e32 v106, v106
	v_rcp_f32_e32 v107, v107
	v_pk_mul_f32 v[36:37], v[36:37], s[100:101] op_sel_hi:[1,0]
	v_exp_f32_e32 v36, v36
	v_pk_mul_f32 v[30:31], v[106:107], v[30:31]
	v_pk_mul_f32 v[106:107], v[134:135], s[100:101] op_sel_hi:[1,0]
	v_exp_f32_e32 v106, v106
	v_exp_f32_e32 v107, v107
	v_exp_f32_e32 v37, v37
	v_mul_f32_e32 v52, 0xbfb8aa3b, v52
	v_pk_add_f32 v[106:107], v[106:107], 1.0 op_sel_hi:[1,0]
	v_rcp_f32_e32 v106, v106
	v_rcp_f32_e32 v107, v107
	v_mul_f32_e32 v53, 0xbfb8aa3b, v53
	v_exp_f32_e32 v52, v52
	v_exp_f32_e32 v53, v53
	v_pk_mul_f32 v[32:33], v[106:107], v[32:33]
	v_pk_mul_f32 v[106:107], v[34:35], s[100:101] op_sel_hi:[1,0]
	v_exp_f32_e32 v106, v106
	v_exp_f32_e32 v107, v107
	v_pk_mul_f32 v[34:35], v[34:35], v[130:131]
	v_add_f32_e32 v36, 1.0, v36
	v_pk_add_f32 v[106:107], v[106:107], 1.0 op_sel_hi:[1,0]
	v_rcp_f32_e32 v106, v106
	v_rcp_f32_e32 v107, v107
	v_add_f32_e32 v37, 1.0, v37
	v_rcp_f32_e32 v36, v36
	v_rcp_f32_e32 v37, v37
	v_pk_mul_f32 v[34:35], v[106:107], v[34:35]
	v_pk_mul_f32 v[106:107], v[38:39], s[100:101] op_sel_hi:[1,0]
	v_exp_f32_e32 v106, v106
	v_exp_f32_e32 v107, v107
	v_pk_add_f32 v[52:53], v[52:53], 1.0 op_sel_hi:[1,0]
	v_pk_add_f32 v[106:107], v[106:107], 1.0 op_sel_hi:[1,0]
	v_rcp_f32_e32 v106, v106
	v_rcp_f32_e32 v107, v107
	v_rcp_f32_e32 v52, v52
	v_rcp_f32_e32 v53, v53
	v_pk_mul_f32 v[36:37], v[36:37], v[108:109]
	v_pk_mul_f32 v[108:109], v[40:41], v[120:121]
	v_pk_mul_f32 v[38:39], v[38:39], v[118:119]
	v_pk_mul_f32 v[40:41], v[40:41], s[100:101] op_sel_hi:[1,0]
	v_pk_mul_f32 v[38:39], v[106:107], v[38:39]
	v_exp_f32_e32 v40, v40
	v_exp_f32_e32 v41, v41
	v_pk_mul_f32 v[106:107], v[50:51], s[100:101] op_sel_hi:[1,0]
	v_pk_mul_f32 v[50:51], v[50:51], v[102:103]
	v_pk_mul_f32 v[52:53], v[52:53], v[104:105]
	v_pk_mul_f32 v[102:103], v[54:55], s[100:101] op_sel_hi:[1,0]
	v_pk_mul_f32 v[104:105], v[56:57], v[116:117]
	v_pk_mul_f32 v[56:57], v[56:57], s[100:101] op_sel_hi:[1,0]
	v_exp_f32_e32 v102, v102
	v_exp_f32_e32 v103, v103
	v_exp_f32_e32 v56, v56
	v_exp_f32_e32 v57, v57
	v_exp_f32_e32 v106, v106
	v_exp_f32_e32 v107, v107
	v_pk_add_f32 v[40:41], v[40:41], 1.0 op_sel_hi:[1,0]
	v_rcp_f32_e32 v40, v40
	v_rcp_f32_e32 v41, v41
	v_pk_add_f32 v[102:103], v[102:103], 1.0 op_sel_hi:[1,0]
	v_pk_add_f32 v[56:57], v[56:57], 1.0 op_sel_hi:[1,0]
	v_rcp_f32_e32 v102, v102
	v_rcp_f32_e32 v103, v103
	v_rcp_f32_e32 v56, v56
	v_rcp_f32_e32 v57, v57
	v_pk_add_f32 v[106:107], v[106:107], 1.0 op_sel_hi:[1,0]
	v_rcp_f32_e32 v106, v106
	v_rcp_f32_e32 v107, v107
	v_pk_mul_f32 v[40:41], v[40:41], v[108:109]
	v_pk_mul_f32 v[54:55], v[54:55], v[114:115]
	v_pk_mul_f32 v[108:109], v[2:3], v[238:239] op_sel_hi:[1,0]
	s_waitcnt vmcnt(0)
	v_pk_mul_f32 v[2:3], v[76:77], v[92:93]
	v_pk_mul_f32 v[54:55], v[102:103], v[54:55]
	v_pk_mul_f32 v[56:57], v[56:57], v[104:105]
	v_pk_mul_f32 v[102:103], v[10:11], v[242:243] op_sel_hi:[1,0]
	v_pk_mul_f32 v[104:105], v[4:5], v[238:239] op_sel_hi:[1,0]
	v_pk_mul_f32 v[4:5], v[74:75], v[90:91]
	v_pk_fma_f32 v[10:11], v[84:85], v[88:89], v[2:3]
	v_pk_fma_f32 v[2:3], v[82:83], v[86:87], v[4:5]
	v_pk_fma_f32 v[4:5], v[104:105], v[80:81], v[10:11]
	v_pk_mul_f32 v[10:11], v[84:85], v[92:93]
	v_pk_mul_f32 v[50:51], v[106:107], v[50:51]
	v_pk_mul_f32 v[106:107], v[14:15], v[240:241] op_sel_hi:[1,0]
	v_pk_mul_f32 v[8:9], v[8:9], v[236:237] op_sel_hi:[1,0]
	v_pk_mul_f32 v[14:15], v[82:83], v[90:91]
	v_pk_fma_f32 v[74:75], v[104:105], v[88:89], v[10:11]
	v_pk_mul_f32 v[76:77], v[104:105], v[92:93]
	v_pk_mul_f32 v[12:13], v[12:13], v[242:243] op_sel_hi:[1,0]
	v_pk_fma_f32 v[10:11], v[108:109], v[86:87], v[14:15]
	v_pk_fma_f32 v[14:15], v[8:9], v[80:81], v[74:75]
	v_pk_fma_f32 v[76:77], v[8:9], v[88:89], v[76:77]
	v_pk_mul_f32 v[8:9], v[8:9], v[92:93]
	v_pk_mul_f32 v[6:7], v[6:7], v[236:237] op_sel_hi:[1,0]
	v_pk_fma_f32 v[8:9], v[12:13], v[88:89], v[8:9]
	v_pk_mul_f32 v[74:75], v[108:109], v[90:91]
	v_pk_fma_f32 v[84:85], v[16:17], v[80:81], v[8:9]
	v_pk_mul_f32 v[8:9], v[12:13], v[92:93]
	v_pk_fma_f32 v[10:11], v[6:7], v[78:79], v[10:11]
	v_pk_fma_f32 v[74:75], v[6:7], v[86:87], v[74:75]
	v_pk_mul_f32 v[6:7], v[6:7], v[90:91]
	v_pk_fma_f32 v[8:9], v[16:17], v[88:89], v[8:9]
	v_pk_fma_f32 v[6:7], v[102:103], v[86:87], v[6:7]
	v_pk_fma_f32 v[104:105], v[48:49], v[80:81], v[8:9]
	v_pk_mul_f32 v[8:9], v[16:17], v[92:93]
	v_pk_fma_f32 v[82:83], v[106:107], v[78:79], v[6:7]
	v_pk_mul_f32 v[6:7], v[102:103], v[90:91]
	v_pk_fma_f32 v[8:9], v[48:49], v[88:89], v[8:9]
	v_pk_fma_f32 v[2:3], v[108:109], v[78:79], v[2:3]
	v_pk_fma_f32 v[6:7], v[106:107], v[86:87], v[6:7]
	v_pk_fma_f32 v[108:109], v[44:45], v[80:81], v[8:9]
	v_pk_mul_f32 v[8:9], v[46:47], v[90:91]
	v_pk_fma_f32 v[74:75], v[102:103], v[78:79], v[74:75]
	v_pk_fma_f32 v[102:103], v[46:47], v[78:79], v[6:7]
	v_pk_mul_f32 v[6:7], v[106:107], v[90:91]
	v_pk_fma_f32 v[8:9], v[42:43], v[86:87], v[8:9]
	v_pk_fma_f32 v[6:7], v[46:47], v[86:87], v[6:7]
	v_pk_fma_f32 v[16:17], v[78:79], v[94:95], v[8:9]
	v_pk_mul_f32 v[8:9], v[86:87], v[94:95]
	v_pk_fma_f32 v[106:107], v[42:43], v[78:79], v[6:7]
	v_pk_fma_f32 v[8:9], v[42:43], v[90:91], v[8:9]
	v_pk_mul_f32 v[42:43], v[124:125], s[100:101] op_sel_hi:[1,0]
	v_exp_f32_e32 v42, v42
	v_exp_f32_e32 v43, v43
	v_pk_mul_f32 v[6:7], v[48:49], v[92:93]
	v_pk_fma_f32 v[76:77], v[12:13], v[80:81], v[76:77]
	v_pk_fma_f32 v[6:7], v[44:45], v[88:89], v[6:7]
	v_pk_add_f32 v[42:43], v[42:43], 1.0 op_sel_hi:[1,0]
	v_pk_fma_f32 v[12:13], v[80:81], v[96:97], v[6:7]
	v_pk_mul_f32 v[6:7], v[88:89], v[96:97]
	v_rcp_f32_e32 v42, v42
	v_rcp_f32_e32 v43, v43
	v_pk_fma_f32 v[6:7], v[44:45], v[92:93], v[6:7]
	v_pk_fma_f32 v[8:9], v[78:79], v[98:99], v[8:9]
	v_pk_fma_f32 v[6:7], v[80:81], v[100:101], v[6:7]
	v_pk_mul_f32 v[46:47], v[180:181], v[106:107]
	v_pk_mul_f32 v[44:45], v[122:123], v[6:7]
	v_pk_mul_f32 v[6:7], v[124:125], v[8:9]
	v_pk_mul_f32 v[8:9], v[122:123], s[100:101] op_sel_hi:[1,0]
	v_pk_mul_f32 v[6:7], v[42:43], v[6:7]
	v_exp_f32_e32 v8, v8
	v_exp_f32_e32 v9, v9
	v_pk_mul_f32 v[42:43], v[128:129], s[100:101] op_sel_hi:[1,0]
	v_exp_f32_e32 v42, v42
	v_exp_f32_e32 v43, v43
	v_pk_add_f32 v[8:9], v[8:9], 1.0 op_sel_hi:[1,0]
	v_rcp_f32_e32 v8, v8
	v_rcp_f32_e32 v9, v9
	v_pk_add_f32 v[42:43], v[42:43], 1.0 op_sel_hi:[1,0]
	v_rcp_f32_e32 v42, v42
	v_rcp_f32_e32 v43, v43
	v_pk_mul_f32 v[8:9], v[8:9], v[44:45]
	v_pk_mul_f32 v[44:45], v[126:127], v[12:13]
	v_pk_mul_f32 v[12:13], v[128:129], v[16:17]
	v_mul_f32_e32 v16, 0xbfb8aa3b, v126
	v_pk_mul_f32 v[12:13], v[42:43], v[12:13]
	v_pk_mul_f32 v[42:43], v[180:181], s[100:101] op_sel_hi:[1,0]
	v_exp_f32_e32 v42, v42
	v_exp_f32_e32 v43, v43
	v_mul_f32_e32 v17, 0xbfb8aa3b, v127
	v_exp_f32_e32 v16, v16
	v_pk_add_f32 v[42:43], v[42:43], 1.0 op_sel_hi:[1,0]
	v_rcp_f32_e32 v42, v42
	v_rcp_f32_e32 v43, v43
	v_exp_f32_e32 v17, v17
	v_add_f32_e32 v16, 1.0, v16
	v_pk_mul_f32 v[14:15], v[62:63], v[14:15]
	v_pk_mul_f32 v[42:43], v[42:43], v[46:47]
	v_pk_mul_f32 v[46:47], v[178:179], s[100:101] op_sel_hi:[1,0]
	v_exp_f32_e32 v46, v46
	v_exp_f32_e32 v47, v47
	v_add_f32_e32 v17, 1.0, v17
	v_pk_mul_f32 v[62:63], v[62:63], s[100:101] op_sel_hi:[1,0]
	v_rcp_f32_e32 v16, v16
	v_rcp_f32_e32 v17, v17
	v_pk_add_f32 v[46:47], v[46:47], 1.0 op_sel_hi:[1,0]
	v_exp_f32_e32 v62, v62
	v_exp_f32_e32 v63, v63
	v_rcp_f32_e32 v46, v46
	v_rcp_f32_e32 v47, v47
	v_pk_mul_f32 v[16:17], v[16:17], v[44:45]
	v_pk_mul_f32 v[44:45], v[178:179], v[108:109]
	v_pk_add_f32 v[62:63], v[62:63], 1.0 op_sel_hi:[1,0]
	v_pk_mul_f32 v[44:45], v[46:47], v[44:45]
	v_pk_mul_f32 v[46:47], v[156:157], s[100:101] op_sel_hi:[1,0]
	v_rcp_f32_e32 v62, v62
	v_rcp_f32_e32 v63, v63
	v_exp_f32_e32 v46, v46
	v_exp_f32_e32 v47, v47
	v_pk_mul_f32 v[78:79], v[156:157], v[102:103]
	v_pk_mul_f32 v[14:15], v[62:63], v[14:15]
	v_pk_mul_f32 v[62:63], v[60:61], s[100:101] op_sel_hi:[1,0]
	v_pk_add_f32 v[46:47], v[46:47], 1.0 op_sel_hi:[1,0]
	v_exp_f32_e32 v62, v62
	v_exp_f32_e32 v63, v63
	v_rcp_f32_e32 v46, v46
	v_rcp_f32_e32 v47, v47
	v_pk_add_f32 v[62:63], v[62:63], 1.0 op_sel_hi:[1,0]
	v_rcp_f32_e32 v62, v62
	v_pk_mul_f32 v[46:47], v[46:47], v[78:79]
	v_pk_mul_f32 v[78:79], v[154:155], s[100:101] op_sel_hi:[1,0]
	v_rcp_f32_e32 v63, v63
	v_exp_f32_e32 v78, v78
	v_exp_f32_e32 v79, v79
	v_pk_mul_f32 v[2:3], v[60:61], v[2:3]
	v_pk_mul_f32 v[48:49], v[154:155], v[104:105]
	v_pk_mul_f32 v[60:61], v[62:63], v[2:3]
	v_pk_mul_f32 v[2:3], v[58:59], s[100:101] op_sel_hi:[1,0]
	v_pk_add_f32 v[78:79], v[78:79], 1.0 op_sel_hi:[1,0]
	v_exp_f32_e32 v2, v2
	v_exp_f32_e32 v3, v3
	v_rcp_f32_e32 v78, v78
	v_rcp_f32_e32 v79, v79
	v_pk_add_f32 v[2:3], v[2:3], 1.0 op_sel_hi:[1,0]
	v_rcp_f32_e32 v2, v2
	v_pk_mul_f32 v[48:49], v[78:79], v[48:49]
	v_pk_mul_f32 v[78:79], v[72:73], s[100:101] op_sel_hi:[1,0]
	v_rcp_f32_e32 v3, v3
	v_exp_f32_e32 v78, v78
	v_exp_f32_e32 v79, v79
	v_pk_mul_f32 v[4:5], v[58:59], v[4:5]
	v_pk_mul_f32 v[80:81], v[70:71], v[84:85]
	v_pk_mul_f32 v[58:59], v[2:3], v[4:5]
	v_cvt_pk_bf16_f32 v4, v6, v7
	v_lshrrev_b32_e32 v130, 2, v213
	v_and_b32_e32 v131, 3, v213
	v_lshlrev_b32_e32 v134, 6, v131
	v_lshl_add_u32 v134, v130, 2, v134
	v_sub_u32_e32 v135, v130, v249
	v_lshl_add_u32 v135, v135, 3, v232
	v_sub_u32_e32 v136, v131, v250
	v_lshl_add_u32 v132, v136, 3, v234
	v_mov_b32_e32 v133, v235
	v_lshlrev_b64 v[132:133], 1, v[132:133]
	v_mov_b64_e32 v[6:7], s[46:47]
	v_add_f32_e32 v78, 1.0, v78
	v_add_f32_e32 v79, 1.0, v79
	v_cvt_pk_bf16_f32 v2, v18, v19
	v_cvt_pk_bf16_f32 v5, v8, v9
	v_mad_i64_i32 v[8:9], s[4:5], v135, s92, v[6:7]
	v_lshlrev_b64 v[18:19], 1, v[234:235]
	v_rcp_f32_e32 v78, v78
	v_rcp_f32_e32 v79, v79
	v_cvt_pk_bf16_f32 v3, v20, v21
	v_lshl_add_u64 v[8:9], v[8:9], 0, v[132:133]
	v_mul_f32_e32 v70, 0xbfb8aa3b, v70
	v_mul_f32_e32 v71, 0xbfb8aa3b, v71
	ds_bpermute_b32 v138, v134, v2
	ds_bpermute_b32 v139, v134, v3
	ds_bpermute_b32 v140, v134, v4
	ds_bpermute_b32 v141, v134, v5
	v_mov_b64_e32 v[146:147], v[8:9]
	v_or_b32_e32 v8, 1, v135
	v_exp_f32_e32 v70, v70
	v_exp_f32_e32 v71, v71
	v_mad_i64_i32 v[8:9], s[4:5], v8, s92, v[6:7]
	v_pk_mul_f32 v[72:73], v[72:73], v[82:83]
	v_cvt_pk_bf16_f32 v2, v22, v23
	v_cvt_pk_bf16_f32 v3, v24, v25
	v_cvt_pk_bf16_f32 v4, v12, v13
	v_cvt_pk_bf16_f32 v5, v16, v17
	v_lshl_add_u64 v[8:9], v[8:9], 0, v[132:133]
	v_pk_mul_f32 v[72:73], v[78:79], v[72:73]
	v_mul_f32_e32 v78, 0xbfb8aa3b, v68
	v_mul_f32_e32 v79, 0xbfb8aa3b, v69
	v_pk_mul_f32 v[76:77], v[66:67], v[76:77]
	v_mul_f32_e32 v66, 0xbfb8aa3b, v66
	v_mul_f32_e32 v67, 0xbfb8aa3b, v67
	ds_bpermute_b32 v142, v134, v2
	ds_bpermute_b32 v143, v134, v3
	ds_bpermute_b32 v144, v134, v4
	ds_bpermute_b32 v145, v134, v5
	v_mov_b64_e32 v[148:149], v[8:9]
	s_waitcnt lgkmcnt(4)
	global_store_dwordx4 v[146:147], v[138:141], off
	v_or_b32_e32 v8, 2, v135
	v_exp_f32_e32 v78, v78
	v_exp_f32_e32 v79, v79
	v_exp_f32_e32 v66, v66
	v_exp_f32_e32 v67, v67
	v_mad_i64_i32 v[8:9], s[4:5], v8, s92, v[6:7]
	v_add_f32_e32 v70, 1.0, v70
	v_add_f32_e32 v71, 1.0, v71
	v_cvt_pk_bf16_f32 v2, v26, v27
	v_cvt_pk_bf16_f32 v3, v28, v29
	v_cvt_pk_bf16_f32 v4, v42, v43
	v_cvt_pk_bf16_f32 v5, v44, v45
	v_lshl_add_u64 v[8:9], v[8:9], 0, v[132:133]
	v_rcp_f32_e32 v70, v70
	v_rcp_f32_e32 v71, v71
	v_pk_mul_f32 v[68:69], v[68:69], v[74:75]
	v_mul_f32_e32 v74, 0xbfb8aa3b, v64
	v_mul_f32_e32 v75, 0xbfb8aa3b, v65
	ds_bpermute_b32 v138, v134, v2
	ds_bpermute_b32 v139, v134, v3
	ds_bpermute_b32 v140, v134, v4
	ds_bpermute_b32 v141, v134, v5
	v_mov_b64_e32 v[146:147], v[8:9]
	s_waitcnt lgkmcnt(4)
	global_store_dwordx4 v[148:149], v[142:145], off
	v_or_b32_e32 v8, 3, v135
	v_exp_f32_e32 v74, v74
	v_exp_f32_e32 v75, v75
	v_mad_i64_i32 v[8:9], s[4:5], v8, s92, v[6:7]
	v_add_f32_e32 v78, 1.0, v78
	v_add_f32_e32 v79, 1.0, v79
	v_add_f32_e32 v66, 1.0, v66
	v_add_f32_e32 v67, 1.0, v67
	v_cvt_pk_bf16_f32 v2, v30, v31
	v_cvt_pk_bf16_f32 v3, v32, v33
	v_cvt_pk_bf16_f32 v4, v46, v47
	v_cvt_pk_bf16_f32 v5, v48, v49
	v_lshl_add_u64 v[8:9], v[8:9], 0, v[132:133]
	v_rcp_f32_e32 v78, v78
	v_rcp_f32_e32 v79, v79
	v_rcp_f32_e32 v66, v66
	v_rcp_f32_e32 v67, v67
	ds_bpermute_b32 v142, v134, v2
	ds_bpermute_b32 v143, v134, v3
	ds_bpermute_b32 v144, v134, v4
	ds_bpermute_b32 v145, v134, v5
	v_mov_b64_e32 v[148:149], v[8:9]
	s_waitcnt lgkmcnt(4)
	global_store_dwordx4 v[146:147], v[138:141], off
	v_or_b32_e32 v8, 4, v135
	v_pk_mul_f32 v[70:71], v[70:71], v[80:81]
	v_mad_i64_i32 v[8:9], s[4:5], v8, s92, v[6:7]
	v_add_f32_e32 v74, 1.0, v74
	v_add_f32_e32 v75, 1.0, v75
	v_cvt_pk_bf16_f32 v2, v34, v35
	v_cvt_pk_bf16_f32 v3, v36, v37
	v_cvt_pk_bf16_f32 v4, v72, v73
	v_cvt_pk_bf16_f32 v5, v70, v71
	v_lshl_add_u64 v[8:9], v[8:9], 0, v[132:133]
	v_rcp_f32_e32 v74, v74
	v_rcp_f32_e32 v75, v75
	ds_bpermute_b32 v138, v134, v2
	ds_bpermute_b32 v139, v134, v3
	ds_bpermute_b32 v140, v134, v4
	ds_bpermute_b32 v141, v134, v5
	v_mov_b64_e32 v[146:147], v[8:9]
	s_waitcnt lgkmcnt(4)
	global_store_dwordx4 v[148:149], v[142:145], off
	v_or_b32_e32 v8, 5, v135
	v_pk_mul_f32 v[68:69], v[78:79], v[68:69]
	v_pk_mul_f32 v[66:67], v[66:67], v[76:77]
	v_mad_i64_i32 v[8:9], s[4:5], v8, s92, v[6:7]
	v_cvt_pk_bf16_f32 v2, v38, v39
	v_cvt_pk_bf16_f32 v3, v40, v41
	v_cvt_pk_bf16_f32 v4, v68, v69
	v_cvt_pk_bf16_f32 v5, v66, v67
	v_lshl_add_u64 v[8:9], v[8:9], 0, v[132:133]
	v_pk_mul_f32 v[10:11], v[64:65], v[10:11]
	ds_bpermute_b32 v142, v134, v2
	ds_bpermute_b32 v143, v134, v3
	ds_bpermute_b32 v144, v134, v4
	ds_bpermute_b32 v145, v134, v5
	v_mov_b64_e32 v[148:149], v[8:9]
	s_waitcnt lgkmcnt(4)
	global_store_dwordx4 v[146:147], v[138:141], off
	v_or_b32_e32 v8, 6, v135
	v_pk_mul_f32 v[10:11], v[74:75], v[10:11]
	v_mad_i64_i32 v[8:9], s[4:5], v8, s92, v[6:7]
	v_cvt_pk_bf16_f32 v2, v50, v51
	v_cvt_pk_bf16_f32 v3, v52, v53
	v_cvt_pk_bf16_f32 v4, v10, v11
	v_cvt_pk_bf16_f32 v5, v14, v15
	v_lshl_add_u64 v[8:9], v[8:9], 0, v[132:133]
	ds_bpermute_b32 v138, v134, v2
	ds_bpermute_b32 v139, v134, v3
	ds_bpermute_b32 v140, v134, v4
	ds_bpermute_b32 v141, v134, v5
	v_mov_b64_e32 v[146:147], v[8:9]
	s_waitcnt lgkmcnt(4)
	global_store_dwordx4 v[148:149], v[142:145], off
	v_or_b32_e32 v8, 7, v135
	v_mad_i64_i32 v[6:7], s[4:5], v8, s92, v[6:7]
	v_cvt_pk_bf16_f32 v2, v54, v55
	v_cvt_pk_bf16_f32 v3, v56, v57
	v_cvt_pk_bf16_f32 v4, v60, v61
	v_cvt_pk_bf16_f32 v5, v58, v59
	v_lshl_add_u64 v[6:7], v[6:7], 0, v[132:133]
	ds_bpermute_b32 v142, v134, v2
	ds_bpermute_b32 v143, v134, v3
	ds_bpermute_b32 v144, v134, v4
	ds_bpermute_b32 v145, v134, v5
	v_mov_b64_e32 v[148:149], v[6:7]
	s_waitcnt lgkmcnt(4)
	global_store_dwordx4 v[146:147], v[138:141], off
	s_andn2_b64 vcc, exec, s[40:41]
	s_waitcnt lgkmcnt(0)
	global_store_dwordx4 v[148:149], v[142:145], off
	s_cbranch_vccnz .LBB0_386
	s_andn2_b64 vcc, exec, s[24:25]
	s_cbranch_vccnz .LBB0_385
	s_barrier
	s_branch .LBB0_385
